# attention K/V staging: loads batched (16/8 in flight) instead of load-wait-write chains
# speedup vs baseline: 1.0820x; 1.0039x over previous
.LBB0_106:
	s_ashr_i32 s0, s2, 4
	s_ashr_i32 s1, s0, 31
	s_lshl_b32 s3, s2, 6
	s_and_b32 s26, s3, 0x3c0
	s_lshl_b64 s[0:1], s[0:1], 19
	s_barrier
	s_and_saveexec_b64 s[20:21], s[38:39]
	s_movk_i32 s33, 0x5ff
	s_cbranch_execz .LBB0_111
	v_readlane_b32 s22, v253, 4
	v_readlane_b32 s23, v253, 5
	s_add_u32 s3, s22, s0
	s_addc_u32 s23, s23, s1
	s_lshl_b32 s22, s26, 1
	s_add_u32 s22, s3, s22
	s_addc_u32 s23, s23, 0
	v_lshl_add_u64 v[0:1], s[22:23], 0, v[178:179]
	v_mov_b32_e32 v2, v192
	v_ashrrev_i32_e32 v8, 3, v2
	v_ashrrev_i32_e32 v9, 31, v8
	v_lshlrev_b64 v[4:5], 11, v[8:9]
	v_lshl_add_u64 v[4:5], v[0:1], 0, v[4:5]
	global_load_dwordx4 v[16:19], v[4:5], off
	v_mad_u64_u32 v[48:49], s[34:35], v8, s43, v[90:91]
	v_add_u32_e32 v2, 0x200, v192
	v_ashrrev_i32_e32 v8, 3, v2
	v_ashrrev_i32_e32 v9, 31, v8
	v_lshlrev_b64 v[4:5], 11, v[8:9]
	v_lshl_add_u64 v[4:5], v[0:1], 0, v[4:5]
	global_load_dwordx4 v[20:23], v[4:5], off
	v_mad_u64_u32 v[50:51], s[34:35], v8, s43, v[90:91]
	v_add_u32_e32 v2, 0x400, v192
	v_ashrrev_i32_e32 v8, 3, v2
	v_ashrrev_i32_e32 v9, 31, v8
	v_lshlrev_b64 v[4:5], 11, v[8:9]
	v_lshl_add_u64 v[4:5], v[0:1], 0, v[4:5]
	global_load_dwordx4 v[24:27], v[4:5], off
	v_mad_u64_u32 v[52:53], s[34:35], v8, s43, v[90:91]
	v_add_u32_e32 v2, 0x600, v192
	v_ashrrev_i32_e32 v8, 3, v2
	v_ashrrev_i32_e32 v9, 31, v8
	v_lshlrev_b64 v[4:5], 11, v[8:9]
	v_lshl_add_u64 v[4:5], v[0:1], 0, v[4:5]
	global_load_dwordx4 v[28:31], v[4:5], off
	v_mad_u64_u32 v[54:55], s[34:35], v8, s43, v[90:91]
	s_ashr_i32 s3, s2, 31
	s_lshl_b64 s[22:23], s[2:3], 15
	v_lshl_add_u64 v[0:1], v[92:93], 0, s[22:23]
	v_mov_b32_e32 v2, v192
	v_ashrrev_i32_e32 v8, 5, v2
	v_ashrrev_i32_e32 v9, 31, v8
	v_lshlrev_b64 v[4:5], 9, v[8:9]
	v_lshl_add_u64 v[4:5], v[0:1], 0, v[4:5]
	global_load_dwordx4 v[32:35], v[4:5], off
	v_mad_u64_u32 v[56:57], s[34:35], v8, s42, v[94:95]
	v_add_u32_e32 v2, 0x200, v192
	v_ashrrev_i32_e32 v8, 5, v2
	v_ashrrev_i32_e32 v9, 31, v8
	v_lshlrev_b64 v[4:5], 9, v[8:9]
	v_lshl_add_u64 v[4:5], v[0:1], 0, v[4:5]
	global_load_dwordx4 v[36:39], v[4:5], off
	v_mad_u64_u32 v[58:59], s[34:35], v8, s42, v[94:95]
	v_add_u32_e32 v2, 0x400, v192
	v_ashrrev_i32_e32 v8, 5, v2
	v_ashrrev_i32_e32 v9, 31, v8
	v_lshlrev_b64 v[4:5], 9, v[8:9]
	v_lshl_add_u64 v[4:5], v[0:1], 0, v[4:5]
	global_load_dwordx4 v[40:43], v[4:5], off
	v_mad_u64_u32 v[60:61], s[34:35], v8, s42, v[94:95]
	v_add_u32_e32 v2, 0x600, v192
	v_ashrrev_i32_e32 v8, 5, v2
	v_ashrrev_i32_e32 v9, 31, v8
	v_lshlrev_b64 v[4:5], 9, v[8:9]
	v_lshl_add_u64 v[4:5], v[0:1], 0, v[4:5]
	global_load_dwordx4 v[44:47], v[4:5], off
	v_mad_u64_u32 v[62:63], s[34:35], v8, s42, v[94:95]
	s_waitcnt vmcnt(7)
	ds_write_b128 v48, v[16:19]
	s_waitcnt vmcnt(6)
	ds_write_b128 v50, v[20:23]
	s_waitcnt vmcnt(5)
	ds_write_b128 v52, v[24:27]
	s_waitcnt vmcnt(4)
	ds_write_b128 v54, v[28:31]
	s_waitcnt vmcnt(3)
	ds_write_b128 v56, v[32:35]
	s_waitcnt vmcnt(2)
	ds_write_b128 v58, v[36:39]
	s_waitcnt vmcnt(1)
	ds_write_b128 v60, v[40:43]
	s_waitcnt vmcnt(0)
	ds_write_b128 v62, v[44:47]

.LBB0_118:
	s_ashr_i32 s2, s63, 6
	s_ashr_i32 s56, s63, 2
	s_ashr_i32 s3, s2, 31
	s_and_b32 s58, s56, 15
	s_lshl_b64 s[2:3], s[2:3], 10
	s_add_u32 s2, s2, 0x2000
	s_addc_u32 s3, s3, 0
	s_lshl_b64 s[20:21], s[2:3], 11
	v_readlane_b32 s22, v253, 4
	v_readlane_b32 s23, v253, 5
	s_add_u32 s20, s22, s20
	s_addc_u32 s21, s23, s21
	s_lshl_b32 s26, s58, 7
	s_add_u32 s34, s20, s26
	s_addc_u32 s35, s21, 0
	s_lshl_b32 s20, s63, 2
	s_and_b32 s22, s20, 12
	v_sub_u32_e64 v0, s22, 4 clamp
	v_lshlrev_b32_e32 v1, 6, v0
	v_add_u32_e32 v2, v1, v108
	v_ashrrev_i32_e32 v3, 31, v2
	v_lshl_add_u64 v[70:71], s[34:35], 0, v[178:179]
	v_lshlrev_b64 v[2:3], 11, v[2:3]
	v_lshl_add_u64 v[2:3], v[70:71], 0, v[2:3]
	s_barrier
	global_load_dwordx4 v[12:15], v[2:3], off
	v_and_b32_e32 v1, 0x100, v1
	s_ashr_i32 s57, s56, 31
	v_add_u32_e32 v6, v1, v108
	s_movk_i32 s59, 0x90
	s_lshl_b64 s[36:37], s[56:57], 17
	v_mad_u64_u32 v[80:81], s[34:35], v6, s59, v[110:111]
	v_lshl_add_u64 v[68:69], v[138:139], 0, s[36:37]
	s_max_u32 s21, s22, 4
	s_lshl_b32 s20, s21, 6
	v_lshl_add_u32 v146, v1, 1, v109
	s_add_i32 s34, s20, 0xffffff40
	s_and_b32 s23, s34, 0x140
	s_mov_b32 s35, s27
	v_mov_b32_e32 v145, s3
	v_lshl_add_u64 v[142:143], v[112:113], 0, s[26:27]
	s_mov_b64 s[0:1], s[90:91]
	v_readlane_b32 s80, v253, 46
	v_readlane_b32 s94, v253, 60
	v_readlane_b32 s95, v253, 61
	v_lshlrev_b32_e32 v97, 2, v122
	v_lshlrev_b32_e32 v95, 2, v126
	v_lshlrev_b32_e32 v93, 2, v124
	v_lshlrev_b32_e32 v98, 2, v118
	v_lshlrev_b32_e32 v92, 2, v128
	v_lshlrev_b32_e32 v99, 2, v114
	v_lshlrev_b32_e32 v96, 2, v116
	v_lshlrev_b32_e32 v94, 2, v120
	v_readlane_b32 s81, v253, 47
	v_readlane_b32 s82, v253, 48
	v_readlane_b32 s83, v253, 49
	v_readlane_b32 s84, v253, 50
	v_readlane_b32 s85, v253, 51
	v_readlane_b32 s86, v253, 52
	v_readlane_b32 s87, v253, 53
	v_readlane_b32 s88, v253, 54
	v_readlane_b32 s89, v253, 55
	v_readlane_b32 s90, v253, 56
	v_readlane_b32 s91, v253, 57
	v_readlane_b32 s92, v253, 58
	v_readlane_b32 s93, v253, 59
	v_lshlrev_b32_e32 v2, 7, v0
	v_mov_b32_e32 v3, v179
	v_lshl_add_u64 v[2:3], v[68:69], 0, v[2:3]
	global_load_dwordx4 v[16:19], v[2:3], off
	v_add_u32_e32 v2, s34, v108
	v_ashrrev_i32_e32 v3, 31, v2
	v_lshlrev_b64 v[2:3], 11, v[2:3]
	v_lshl_add_u64 v[2:3], v[70:71], 0, v[2:3]
	global_load_dwordx4 v[20:23], v[2:3], off
	v_add_u32_e32 v1, s23, v108
	v_mad_u64_u32 v[82:83], s[36:37], v1, s59, v[110:111]
	v_lshl_add_u32 v147, s23, 1, v109
	v_lshl_add_u64 v[2:3], s[34:35], 1, v[68:69]
	global_load_dwordx4 v[24:27], v[2:3], off
	s_add_i32 s34, s20, 0xffffff80
	s_and_b32 s23, s34, 0x180
	v_add_u32_e32 v2, s34, v108
	v_ashrrev_i32_e32 v3, 31, v2
	v_lshlrev_b64 v[2:3], 11, v[2:3]
	v_lshl_add_u64 v[2:3], v[70:71], 0, v[2:3]
	global_load_dwordx4 v[28:31], v[2:3], off
	v_add_u32_e32 v1, s23, v108
	v_mad_u64_u32 v[84:85], s[36:37], v1, s59, v[110:111]
	v_lshl_add_u32 v148, s23, 1, v109
	v_lshl_add_u64 v[2:3], s[34:35], 1, v[68:69]
	global_load_dwordx4 v[32:35], v[2:3], off
	s_sub_i32 s34, s20, 64
	s_and_b32 s23, s34, 0x1c0
	v_add_u32_e32 v2, s34, v108
	v_ashrrev_i32_e32 v3, 31, v2
	v_lshlrev_b64 v[2:3], 11, v[2:3]
	v_lshl_add_u64 v[2:3], v[70:71], 0, v[2:3]
	global_load_dwordx4 v[36:39], v[2:3], off
	v_add_u32_e32 v1, s23, v108
	v_mad_u64_u32 v[86:87], s[36:37], v1, s59, v[110:111]
	v_lshl_add_u32 v149, s23, 1, v109
	s_and_b32 s23, s20, 0x100
	v_lshl_add_u64 v[2:3], s[34:35], 1, v[68:69]
	global_load_dwordx4 v[40:43], v[2:3], off
	v_add_u32_e32 v2, s20, v108
	v_ashrrev_i32_e32 v3, 31, v2
	v_lshlrev_b64 v[2:3], 11, v[2:3]
	v_lshl_add_u64 v[2:3], v[70:71], 0, v[2:3]
	global_load_dwordx4 v[44:47], v[2:3], off
	v_add_u32_e32 v1, s23, v108
	v_mad_u64_u32 v[100:101], s[34:35], v1, s59, v[110:111]
	s_lshl_b32 s34, s21, 7
	s_mov_b32 s35, s27
	v_lshl_add_u32 v150, s23, 1, v109
	s_or_b32 s21, s20, 64
	v_lshl_add_u64 v[6:7], v[68:69], 0, s[34:35]
	global_load_dwordx4 v[48:51], v[6:7], off
	v_add_u32_e32 v2, s21, v108
	v_ashrrev_i32_e32 v3, 31, v2
	v_lshlrev_b64 v[2:3], 11, v[2:3]
	v_lshl_add_u64 v[2:3], v[70:71], 0, v[2:3]
	global_load_dwordx4 v[52:55], v[2:3], off
	s_and_b32 s21, s21, 0x140
	v_add_u32_e32 v1, s21, v108
	v_mad_u64_u32 v[102:103], s[34:35], v1, s59, v[110:111]
	v_lshl_add_u32 v151, s21, 1, v109
	s_or_b32 s21, s20, 0x80
	s_or_b32 s20, s20, 0xc0
	global_load_dwordx4 v[56:59], v[6:7], off offset:128
	v_add_u32_e32 v2, s21, v108
	v_ashrrev_i32_e32 v3, 31, v2
	v_lshlrev_b64 v[2:3], 11, v[2:3]
	v_lshl_add_u64 v[2:3], v[70:71], 0, v[2:3]
	global_load_dwordx4 v[60:63], v[2:3], off
	s_and_b32 s21, s21, 0x180
	v_add_u32_e32 v1, s21, v108
	v_mad_u64_u32 v[104:105], s[34:35], v1, s59, v[110:111]
	v_lshl_add_u32 v152, s21, 1, v109
	global_load_dwordx4 v[64:67], v[6:7], off offset:256
	v_add_u32_e32 v2, s20, v108
	v_ashrrev_i32_e32 v3, 31, v2
	v_lshlrev_b64 v[2:3], 11, v[2:3]
	v_lshl_add_u64 v[2:3], v[70:71], 0, v[2:3]
	global_load_dwordx4 v[72:75], v[2:3], off
	s_and_b32 s20, s20, 0x1c0
	v_add_u32_e32 v1, s20, v108
	v_mad_u64_u32 v[106:107], s[34:35], v1, s59, v[110:111]
	v_lshl_add_u32 v153, s20, 1, v109
	s_mul_i32 s20, s58, 0x744
	s_add_u32 s36, s94, s20
	v_readfirstlane_b32 s20, v0
	s_addc_u32 s23, s95, 0
	s_add_i32 s20, s20, s61
	s_sub_i32 s21, s20, s22
	s_lshl_b32 s20, s20, 6
	s_and_b32 s35, s20, 0x100
	v_or_b32_e32 v0, s35, v115
	s_or_b32 s34, s35, 64
	s_or_b32 s33, s35, 0x80
	s_or_b32 s26, s35, 0xc0
	s_mul_i32 s20, s21, 31
	s_ashr_i32 s21, s20, 31
	s_lshl_b64 s[20:21], s[20:21], 2
	s_add_u32 s20, s36, s20
	s_addc_u32 s21, s23, s21
	global_load_dwordx4 v[76:79], v[6:7], off offset:384
	s_waitcnt vmcnt(15)
	ds_write_b128 v80, v[12:15]
	s_waitcnt vmcnt(14)
	ds_write_b128 v146, v[16:19]
	s_waitcnt vmcnt(13)
	ds_write_b128 v82, v[20:23]
	s_waitcnt vmcnt(12)
	ds_write_b128 v147, v[24:27]
	s_waitcnt vmcnt(11)
	ds_write_b128 v84, v[28:31]
	s_waitcnt vmcnt(10)
	ds_write_b128 v148, v[32:35]
	s_waitcnt vmcnt(9)
	ds_write_b128 v86, v[36:39]
	s_waitcnt vmcnt(8)
	ds_write_b128 v149, v[40:43]
	s_waitcnt vmcnt(7)
	ds_write_b128 v100, v[44:47]
	s_waitcnt vmcnt(6)
	ds_write_b128 v150, v[48:51]
	s_waitcnt vmcnt(5)
	ds_write_b128 v102, v[52:55]
	s_waitcnt vmcnt(4)
	ds_write_b128 v151, v[56:59]
	s_waitcnt vmcnt(3)
	ds_write_b128 v104, v[60:63]
	s_waitcnt vmcnt(2)
	ds_write_b128 v152, v[64:67]
	s_waitcnt vmcnt(1)
	ds_write_b128 v106, v[72:75]
	s_waitcnt vmcnt(0)
	ds_write_b128 v153, v[76:79]
	v_lshl_or_b32 v1, s22, 6, v111
	v_or_b32_e32 v144, s2, v1
	v_lshlrev_b64 v[140:141], 11, v[144:145]
	v_lshl_add_u64 v[88:89], v[142:143], 0, v[140:141]
	s_waitcnt lgkmcnt(0)
	s_barrier
	global_load_dwordx4 v[20:23], v[88:89], off
	global_load_dwordx4 v[24:27], v[88:89], off offset:64
	v_mad_u32_u24 v4, v0, s59, v117
	ds_read_b128 v[0:3], v4
	ds_read_b128 v[4:7], v4 offset:64
	s_waitcnt vmcnt(1) lgkmcnt(1)
	v_mfma_f32_16x16x32_bf16 v[0:3], v[0:3], v[20:23], 0
	s_waitcnt vmcnt(0) lgkmcnt(0)
	v_mfma_f32_16x16x32_bf16 v[28:31], v[4:7], v[24:27], v[0:3]
	s_nop 5
	v_or_b32_e32 v0, s35, v119
	v_mad_u32_u24 v4, v0, s59, v117
	ds_read_b128 v[0:3], v4
	ds_read_b128 v[4:7], v4 offset:64
	s_waitcnt lgkmcnt(1)
	v_mfma_f32_16x16x32_bf16 v[0:3], v[0:3], v[20:23], 0
	s_waitcnt lgkmcnt(0)
	v_mfma_f32_16x16x32_bf16 v[32:35], v[4:7], v[24:27], v[0:3]
	s_nop 5
	v_add_u32_e32 v0, s34, v115
	v_mad_u32_u24 v4, v0, s59, v117
	ds_read_b128 v[0:3], v4
	ds_read_b128 v[4:7], v4 offset:64
	s_waitcnt lgkmcnt(1)
	v_mfma_f32_16x16x32_bf16 v[0:3], v[0:3], v[20:23], 0
	s_waitcnt lgkmcnt(0)
	v_mfma_f32_16x16x32_bf16 v[36:39], v[4:7], v[24:27], v[0:3]
	s_nop 5
	v_add_u32_e32 v0, s34, v119
	v_mad_u32_u24 v4, v0, s59, v117
	ds_read_b128 v[0:3], v4
	ds_read_b128 v[4:7], v4 offset:64
	s_waitcnt lgkmcnt(1)
	v_mfma_f32_16x16x32_bf16 v[0:3], v[0:3], v[20:23], 0
	s_waitcnt lgkmcnt(0)
	v_mfma_f32_16x16x32_bf16 v[16:19], v[4:7], v[24:27], v[0:3]
	s_nop 5
	v_or_b32_e32 v0, s33, v115
	v_mad_u32_u24 v4, v0, s59, v117
	ds_read_b128 v[0:3], v4
	ds_read_b128 v[4:7], v4 offset:64
	s_waitcnt lgkmcnt(1)
	v_mfma_f32_16x16x32_bf16 v[0:3], v[0:3], v[20:23], 0
	s_waitcnt lgkmcnt(0)
	v_mfma_f32_16x16x32_bf16 v[12:15], v[4:7], v[24:27], v[0:3]
	s_nop 5
	v_add_u32_e32 v0, s33, v119
	v_mad_u32_u24 v4, v0, s59, v117
	ds_read_b128 v[0:3], v4
	ds_read_b128 v[4:7], v4 offset:64
	s_waitcnt lgkmcnt(1)
	v_mfma_f32_16x16x32_bf16 v[0:3], v[0:3], v[20:23], 0
	s_waitcnt lgkmcnt(0)
	v_mfma_f32_16x16x32_bf16 v[8:11], v[4:7], v[24:27], v[0:3]
	s_nop 5
	v_add_u32_e32 v0, s26, v115
	v_mad_u32_u24 v4, v0, s59, v117
	ds_read_b128 v[0:3], v4
	ds_read_b128 v[4:7], v4 offset:64
	s_waitcnt lgkmcnt(1)
	v_mfma_f32_16x16x32_bf16 v[0:3], v[0:3], v[20:23], 0
	s_waitcnt lgkmcnt(0)
	v_mfma_f32_16x16x32_bf16 v[4:7], v[4:7], v[24:27], v[0:3]
	s_nop 5
	v_add_u32_e32 v0, s26, v119
	v_mad_u32_u24 v40, v0, s59, v117
	ds_read_b128 v[0:3], v40
	ds_read_b128 v[40:43], v40 offset:64
	s_waitcnt lgkmcnt(1)
	v_mfma_f32_16x16x32_bf16 v[0:3], v[0:3], v[20:23], 0
	global_load_dword v22, v98, s[20:21] offset:868
	global_load_dword v20, v99, s[20:21] offset:868
	s_waitcnt lgkmcnt(0)
	v_mfma_f32_16x16x32_bf16 v[0:3], v[40:43], v[24:27], v[0:3]
	global_load_dword v24, v97, s[20:21] offset:868
	global_load_dword v26, v95, s[20:21] offset:868
	global_load_dword v25, v93, s[20:21] offset:868
	global_load_dword v21, v96, s[20:21] offset:868
	s_waitcnt vmcnt(3)
	v_fmamk_f32 v24, v24, 0x3fb8aa3b, v32
	global_load_dword v32, v97, s[20:21] offset:992
	v_cndmask_b32_e64 v24, v220, v24, s[46:47]
	s_waitcnt vmcnt(0)
	v_fmamk_f32 v16, v32, 0x3fb8aa3b, v16
	global_load_dword v32, v93, s[20:21] offset:992
	v_fmamk_f32 v26, v26, 0x3fb8aa3b, v34
	v_cndmask_b32_e64 v27, v220, v26, s[50:51]
	global_load_dword v26, v92, s[20:21] offset:868
	v_cndmask_b32_e64 v16, v220, v16, s[46:47]
	s_waitcnt vmcnt(1)
	v_fmamk_f32 v17, v32, 0x3fb8aa3b, v17
	global_load_dword v32, v95, s[20:21] offset:992
	v_fmamk_f32 v22, v22, 0x3fb8aa3b, v30
	global_load_dword v30, v98, s[20:21] offset:992
	v_cndmask_b32_e64 v23, v220, v22, s[42:43]
	global_load_dword v22, v94, s[20:21] offset:868
	v_cndmask_b32_e64 v17, v220, v17, s[48:49]
	s_waitcnt vmcnt(2)
	v_fmamk_f32 v18, v32, 0x3fb8aa3b, v18
	v_cndmask_b32_e64 v32, v220, v18, s[50:51]
	global_load_dword v18, v92, s[20:21] offset:992
	v_fmac_f32_e32 v35, 0x3fb8aa3b, v26
	v_fmamk_f32 v25, v25, 0x3fb8aa3b, v33
	v_cndmask_b32_e64 v26, v220, v35, s[52:53]
	v_cndmask_b32_e64 v25, v220, v25, s[48:49]
	v_max_f32_e32 v33, v27, v26
	v_max3_f32 v33, v24, v25, v33
	s_waitcnt vmcnt(0)
	v_fmac_f32_e32 v19, 0x3fb8aa3b, v18
	v_cndmask_b32_e64 v18, v220, v19, s[52:53]
	global_load_dword v19, v99, s[20:21] offset:1116
	v_max_f32_e32 v34, v32, v18
	v_max3_f32 v34, v16, v17, v34
	s_waitcnt vmcnt(0)
	v_fmamk_f32 v12, v19, 0x3fb8aa3b, v12
	global_load_dword v19, v96, s[20:21] offset:1116
	v_cndmask_b32_e64 v12, v220, v12, s[38:39]
	s_waitcnt vmcnt(0)
	v_fmamk_f32 v13, v19, 0x3fb8aa3b, v13
	global_load_dword v19, v98, s[20:21] offset:1116
	v_cndmask_b32_e64 v13, v220, v13, s[40:41]
	s_waitcnt vmcnt(0)
	v_fmamk_f32 v14, v19, 0x3fb8aa3b, v14
	v_cndmask_b32_e64 v19, v220, v14, s[42:43]
	global_load_dword v14, v94, s[20:21] offset:1116
	v_fmamk_f32 v30, v30, 0x3fb8aa3b, v38
	s_waitcnt vmcnt(0)
	v_fmac_f32_e32 v15, 0x3fb8aa3b, v14
	v_cndmask_b32_e64 v14, v220, v15, s[44:45]
	global_load_dword v15, v97, s[20:21] offset:1116
	s_waitcnt vmcnt(0)
	v_fmamk_f32 v8, v15, 0x3fb8aa3b, v8
	global_load_dword v15, v93, s[20:21] offset:1116
	v_fmamk_f32 v21, v21, 0x3fb8aa3b, v29
	global_load_dword v29, v96, s[20:21] offset:992
	v_cndmask_b32_e64 v21, v220, v21, s[40:41]
	v_cndmask_b32_e64 v8, v220, v8, s[46:47]
	s_waitcnt vmcnt(1)
	v_fmamk_f32 v9, v15, 0x3fb8aa3b, v9
	global_load_dword v15, v95, s[20:21] offset:1116
	v_cndmask_b32_e64 v9, v220, v9, s[48:49]
	s_waitcnt vmcnt(0)
	v_fmamk_f32 v10, v15, 0x3fb8aa3b, v10
	v_cndmask_b32_e64 v15, v220, v10, s[50:51]
	global_load_dword v10, v92, s[20:21] offset:1116
	v_fmac_f32_e32 v31, 0x3fb8aa3b, v22
	v_cndmask_b32_e64 v22, v220, v31, s[44:45]
	v_cndmask_b32_e64 v31, v220, v30, s[42:43]
	global_load_dword v30, v94, s[20:21] offset:992
	s_waitcnt vmcnt(1)
	v_fmac_f32_e32 v11, 0x3fb8aa3b, v10
	v_cndmask_b32_e64 v10, v220, v11, s[52:53]
	global_load_dword v11, v99, s[20:21] offset:1240
	s_waitcnt vmcnt(0)
	v_fmamk_f32 v4, v11, 0x3fb8aa3b, v4
	global_load_dword v11, v96, s[20:21] offset:1240
	v_cndmask_b32_e64 v4, v220, v4, s[38:39]
	s_waitcnt vmcnt(0)
	v_fmamk_f32 v5, v11, 0x3fb8aa3b, v5
	global_load_dword v11, v98, s[20:21] offset:1240
	v_cndmask_b32_e64 v5, v220, v5, s[40:41]
	s_waitcnt vmcnt(0)
	v_fmamk_f32 v6, v11, 0x3fb8aa3b, v6
	global_load_dword v11, v94, s[20:21] offset:1240
	v_fmamk_f32 v20, v20, 0x3fb8aa3b, v28
	global_load_dword v28, v99, s[20:21] offset:992
	v_cndmask_b32_e64 v20, v220, v20, s[38:39]
	v_cndmask_b32_e64 v6, v220, v6, s[42:43]
	s_waitcnt vmcnt(1)
	v_fmac_f32_e32 v7, 0x3fb8aa3b, v11
	global_load_dword v11, v97, s[20:21] offset:1240
	v_cndmask_b32_e64 v7, v220, v7, s[44:45]
	s_waitcnt vmcnt(0)
	v_fmamk_f32 v0, v11, 0x3fb8aa3b, v0
	global_load_dword v11, v93, s[20:21] offset:1240
	v_fmamk_f32 v29, v29, 0x3fb8aa3b, v37
	v_cndmask_b32_e64 v29, v220, v29, s[40:41]
	v_cndmask_b32_e64 v0, v220, v0, s[46:47]
	s_waitcnt vmcnt(0)
	v_fmamk_f32 v1, v11, 0x3fb8aa3b, v1
	global_load_dword v11, v95, s[20:21] offset:1240
	v_fmamk_f32 v28, v28, 0x3fb8aa3b, v36
	v_cndmask_b32_e64 v28, v220, v28, s[38:39]
	v_cndmask_b32_e64 v1, v220, v1, s[48:49]
	s_waitcnt vmcnt(0)
	v_fmamk_f32 v2, v11, 0x3fb8aa3b, v2
	global_load_dword v11, v92, s[20:21] offset:1240
	v_fmac_f32_e32 v39, 0x3fb8aa3b, v30
	v_cndmask_b32_e64 v30, v220, v39, s[44:45]
	s_mov_b32 s20, 0xf149f2ca
	v_cndmask_b32_e64 v2, v220, v2, s[50:51]
	s_waitcnt vmcnt(0)
	v_fmac_f32_e32 v3, 0x3fb8aa3b, v11
	v_max_f32_e32 v11, v23, v22
	v_max3_f32 v11, v20, v21, v11
	v_max3_f32 v11, v11, s20, v33
	v_max_f32_e32 v33, v31, v30
	v_max3_f32 v33, v28, v29, v33
	v_max3_f32 v11, v11, v33, v34
	v_max_f32_e32 v33, v19, v14
	v_max_f32_e32 v34, v15, v10
	v_cndmask_b32_e64 v3, v220, v3, s[52:53]
	v_max3_f32 v33, v12, v13, v33
	v_max3_f32 v34, v8, v9, v34
	v_max3_f32 v11, v11, v33, v34
	v_max_f32_e32 v33, v6, v7
	v_max_f32_e32 v34, v2, v3
	v_max3_f32 v33, v4, v5, v33
	v_max3_f32 v34, v0, v1, v34
	v_max3_f32 v11, v11, v33, v34
	v_and_b32_e32 v34, 64, v219
	v_xor_b32_e32 v33, 16, v219
	v_add_u32_e32 v34, 64, v34
	v_cmp_lt_i32_e32 vcc, v33, v34
	s_nop 1
	v_cndmask_b32_e32 v33, v219, v33, vcc
	v_lshlrev_b32_e32 v145, 2, v33
	ds_bpermute_b32 v33, v145, v11
	s_waitcnt lgkmcnt(0)
	v_max_f32_e32 v33, v33, v33
	v_max_f32_e32 v11, v11, v33
	v_xor_b32_e32 v33, 32, v219
	v_cmp_lt_i32_e32 vcc, v33, v34
	s_nop 1
	v_cndmask_b32_e32 v33, v219, v33, vcc
	v_lshlrev_b32_e32 v149, 2, v33
	ds_bpermute_b32 v33, v149, v11
	s_waitcnt lgkmcnt(0)
	v_max3_f32 v146, v11, v33, s20
	v_sub_f32_e32 v20, v20, v146
	v_exp_f32_e32 v33, v20
	v_sub_f32_e32 v21, v21, v146
	v_exp_f32_e32 v34, v21
	v_sub_f32_e32 v21, v23, v146
	v_exp_f32_e32 v35, v21
	v_sub_f32_e32 v21, v22, v146
	v_exp_f32_e32 v36, v21
	v_sub_f32_e32 v21, v24, v146
	v_add_f32_e32 v20, 0, v33
	v_exp_f32_e32 v24, v21
	v_sub_f32_e32 v21, v25, v146
	v_add_f32_e32 v20, v34, v20
	v_exp_f32_e32 v25, v21
	v_sub_f32_e32 v21, v27, v146
	v_add_f32_e32 v20, v35, v20
	v_exp_f32_e32 v27, v21
	v_sub_f32_e32 v21, v26, v146
	v_add_f32_e32 v20, v36, v20
	v_exp_f32_e32 v26, v21
	v_sub_f32_e32 v21, v28, v146
	v_add_f32_e32 v20, v24, v20
	v_exp_f32_e32 v28, v21
	v_sub_f32_e32 v21, v29, v146
	v_add_f32_e32 v20, v25, v20
	v_exp_f32_e32 v29, v21
	v_sub_f32_e32 v21, v31, v146
	v_add_f32_e32 v20, v27, v20
	v_exp_f32_e32 v31, v21
	v_sub_f32_e32 v21, v30, v146
	v_add_f32_e32 v20, v26, v20
	v_exp_f32_e32 v30, v21
	v_sub_f32_e32 v16, v16, v146
	v_add_f32_e32 v20, v28, v20
	v_exp_f32_e32 v37, v16
	v_sub_f32_e32 v17, v17, v146
	v_add_f32_e32 v20, v29, v20
	v_exp_f32_e32 v38, v17
	v_sub_f32_e32 v17, v32, v146
	v_add_f32_e32 v20, v31, v20
	v_exp_f32_e32 v32, v17
	v_sub_f32_e32 v17, v18, v146
	v_add_f32_e32 v20, v30, v20
	v_exp_f32_e32 v39, v17
	v_sub_f32_e32 v12, v12, v146
	v_add_f32_e32 v16, v37, v20
	v_exp_f32_e32 v40, v12
	v_sub_f32_e32 v13, v13, v146
	v_add_f32_e32 v16, v38, v16
	v_exp_f32_e32 v41, v13
	v_sub_f32_e32 v13, v19, v146
	v_add_f32_e32 v16, v32, v16
	v_exp_f32_e32 v42, v13
	v_sub_f32_e32 v13, v14, v146
	v_add_f32_e32 v16, v39, v16
	v_exp_f32_e32 v43, v13
	v_sub_f32_e32 v8, v8, v146
	v_add_f32_e32 v12, v40, v16
	v_exp_f32_e32 v44, v8
	v_sub_f32_e32 v9, v9, v146
	v_add_f32_e32 v12, v41, v12
	v_exp_f32_e32 v45, v9
	v_sub_f32_e32 v9, v15, v146
	v_add_f32_e32 v12, v42, v12
	v_exp_f32_e32 v46, v9
	v_sub_f32_e32 v9, v10, v146
	v_add_f32_e32 v12, v43, v12
	v_exp_f32_e32 v47, v9
	v_sub_f32_e32 v4, v4, v146
	v_add_f32_e32 v8, v44, v12
	v_exp_f32_e32 v48, v4
	v_sub_f32_e32 v5, v5, v146
	v_add_f32_e32 v8, v45, v8
	v_exp_f32_e32 v49, v5
	v_sub_f32_e32 v5, v6, v146
	v_add_f32_e32 v8, v46, v8
	v_exp_f32_e32 v50, v5
	v_sub_f32_e32 v5, v7, v146
	v_add_f32_e32 v8, v47, v8
	v_exp_f32_e32 v51, v5
	v_sub_f32_e32 v0, v0, v146
	v_add_f32_e32 v4, v48, v8
	v_exp_f32_e32 v52, v0
	v_sub_f32_e32 v1, v1, v146
	v_add_f32_e32 v4, v49, v4
	v_exp_f32_e32 v53, v1
	v_sub_f32_e32 v1, v2, v146
	v_add_f32_e32 v4, v50, v4
	v_exp_f32_e32 v54, v1
	v_sub_f32_e32 v1, v3, v146
	v_add_f32_e32 v4, v51, v4
	v_exp_f32_e32 v55, v1
	v_add_f32_e32 v0, v52, v4
	v_add_f32_e32 v0, v53, v0
	v_add_f32_e32 v0, v54, v0
	v_add_f32_e32 v0, v55, v0
	v_sub_f32_e32 v11, 0xf149f2ca, v146
	ds_bpermute_b32 v2, v145, v0
	v_exp_f32_e32 v1, v11
	s_or_b32 s20, s35, s60
	v_lshl_add_u32 v16, s20, 1, v121
	v_add_u32_e32 v12, v16, v123
	s_waitcnt lgkmcnt(0)
	v_add_f32_e32 v90, v0, v2
	v_mul_f32_e32 v20, 0, v1
	v_cvt_pk_bf16_f32 v0, v33, v34
	v_cvt_pk_bf16_f32 v1, v35, v36
	v_cvt_pk_bf16_f32 v2, v24, v25
	v_cvt_pk_bf16_f32 v3, v27, v26
	ds_read2_b64 v[4:7], v12 offset1:4
	v_add_u32_e32 v8, 0x4000, v12
	v_add_u32_e32 v12, 0x8000, v12
	v_add_u32_e32 v16, v16, v125
	ds_read2_b64 v[8:11], v8 offset0:32 offset1:36
	ds_read2_b64 v[12:15], v12 offset0:64 offset1:68
	ds_read2_b64 v[16:19], v16 offset1:4
	v_mov_b32_e32 v21, v20
	v_mov_b32_e32 v22, v20
	v_mov_b32_e32 v23, v20
	s_or_b32 s20, s34, s60
	ds_bpermute_b32 v91, v149, v90
	s_waitcnt lgkmcnt(4)
	v_mfma_f32_16x16x32_bf16 v[4:7], v[4:7], v[0:3], v[20:23]
	s_waitcnt lgkmcnt(3)
	v_mfma_f32_16x16x32_bf16 v[8:11], v[8:11], v[0:3], v[20:23]
	s_waitcnt lgkmcnt(2)
	v_mfma_f32_16x16x32_bf16 v[12:15], v[12:15], v[0:3], v[20:23]
	s_waitcnt lgkmcnt(1)
	v_mfma_f32_16x16x32_bf16 v[0:3], v[16:19], v[0:3], v[20:23]
	v_cvt_pk_bf16_f32 v16, v28, v29
	v_cvt_pk_bf16_f32 v17, v31, v30
	v_cvt_pk_bf16_f32 v18, v37, v38
	v_cvt_pk_bf16_f32 v19, v32, v39
	s_nop 2
	v_lshl_add_u32 v21, s20, 1, v121
	v_add_u32_e32 v26, v21, v123
	ds_read2_b64 v[22:25], v26 offset1:4
	s_waitcnt lgkmcnt(0)
	v_mfma_f32_16x16x32_bf16 v[4:7], v[22:25], v[16:19], v[4:7]
	v_add_u32_e32 v22, 0x4000, v26
	ds_read2_b64 v[22:25], v22 offset0:32 offset1:36
	v_add_u32_e32 v21, v21, v125
	s_waitcnt lgkmcnt(0)
	v_mfma_f32_16x16x32_bf16 v[8:11], v[22:25], v[16:19], v[8:11]
	v_add_u32_e32 v22, 0x8000, v26
	ds_read2_b64 v[22:25], v22 offset0:64 offset1:68
	s_or_b32 s20, s33, s60
	s_waitcnt lgkmcnt(0)
	v_mfma_f32_16x16x32_bf16 v[12:15], v[22:25], v[16:19], v[12:15]
	ds_read2_b64 v[22:25], v21 offset1:4
	v_lshl_add_u32 v21, s20, 1, v121
	v_add_u32_e32 v26, v21, v123
	s_waitcnt lgkmcnt(0)
	v_mfma_f32_16x16x32_bf16 v[0:3], v[22:25], v[16:19], v[0:3]
	v_cvt_pk_bf16_f32 v16, v40, v41
	v_cvt_pk_bf16_f32 v17, v42, v43
	v_cvt_pk_bf16_f32 v18, v44, v45
	v_cvt_pk_bf16_f32 v19, v46, v47
	ds_read2_b64 v[22:25], v26 offset1:4
	s_waitcnt lgkmcnt(0)
	v_mfma_f32_16x16x32_bf16 v[4:7], v[22:25], v[16:19], v[4:7]
	v_add_u32_e32 v22, 0x4000, v26
	ds_read2_b64 v[22:25], v22 offset0:32 offset1:36
	v_add_u32_e32 v21, v21, v125
	s_waitcnt lgkmcnt(0)
	v_mfma_f32_16x16x32_bf16 v[8:11], v[22:25], v[16:19], v[8:11]
	v_add_u32_e32 v22, 0x8000, v26
	ds_read2_b64 v[22:25], v22 offset0:64 offset1:68
	s_or_b32 s20, s26, s60
	s_waitcnt lgkmcnt(0)
	v_mfma_f32_16x16x32_bf16 v[12:15], v[22:25], v[16:19], v[12:15]
	ds_read2_b64 v[22:25], v21 offset1:4
	v_lshl_add_u32 v21, s20, 1, v121
	v_add_u32_e32 v26, v21, v123
	s_waitcnt lgkmcnt(0)
	v_mfma_f32_16x16x32_bf16 v[0:3], v[22:25], v[16:19], v[0:3]
	v_cvt_pk_bf16_f32 v16, v48, v49
	v_cvt_pk_bf16_f32 v17, v50, v51
	v_cvt_pk_bf16_f32 v18, v52, v53
	v_cvt_pk_bf16_f32 v19, v54, v55
	ds_read2_b64 v[22:25], v26 offset1:4
	s_waitcnt lgkmcnt(0)
	v_mfma_f32_16x16x32_bf16 v[4:7], v[22:25], v[16:19], v[4:7]
	v_add_u32_e32 v22, 0x4000, v26
	ds_read2_b64 v[22:25], v22 offset0:32 offset1:36
	v_add_u32_e32 v21, v21, v125
	s_waitcnt lgkmcnt(0)
	v_mfma_f32_16x16x32_bf16 v[8:11], v[22:25], v[16:19], v[8:11]
	v_add_u32_e32 v22, 0x8000, v26
	ds_read2_b64 v[22:25], v22 offset0:64 offset1:68
	s_or_b32 s20, s22, 1
	s_waitcnt lgkmcnt(0)
	v_mfma_f32_16x16x32_bf16 v[12:15], v[22:25], v[16:19], v[12:15]
	ds_read2_b64 v[22:25], v21 offset1:4
	s_waitcnt lgkmcnt(0)
	v_mfma_f32_16x16x32_bf16 v[16:19], v[22:25], v[16:19], v[0:3]
	s_nop 2
	v_sub_u32_e64 v0, s20, 4 clamp
	s_nop 0
	v_readfirstlane_b32 s21, v0
	s_min_u32 s21, s21, 8
	v_sub_u32_e64 v0, s20, 5 clamp
	v_cmp_ne_u32_e32 vcc, s21, v0
	s_cbranch_vccz .LBB0_120
	s_lshl_b32 s26, s21, 6
	s_add_i32 s33, s26, 0x1c0
	v_add_u32_e32 v0, s33, v108
	v_ashrrev_i32_e32 v1, 31, v0
	v_lshlrev_b64 v[0:1], 11, v[0:1]
	s_lshl_b32 s26, s21, 7
	v_lshl_add_u64 v[0:1], v[70:71], 0, v[0:1]
	v_lshl_add_u64 v[22:23], v[68:69], 0, s[26:27]
	s_barrier
	global_load_dwordx4 v[0:3], v[0:1], off
	s_nop 0
	global_load_dwordx4 v[22:25], v[22:23], off offset:896
	s_and_b32 s26, s33, 0x1c0
	v_add_u32_e32 v21, s26, v108
	v_mad_u64_u32 v[26:27], s[34:35], v21, s59, v[110:111]
	v_lshl_add_u32 v28, s26, 1, v109
	s_waitcnt vmcnt(1)
	ds_write_b128 v26, v[0:3]
	s_waitcnt vmcnt(0)
	ds_write_b128 v28, v[22:25]
	s_waitcnt lgkmcnt(0)
	s_barrier

.LBB0_124:
	v_lshl_or_b32 v1, s20, 6, v111
	v_or_b32_e32 v2, s2, v1
	v_mov_b32_e32 v3, s3
	v_lshlrev_b64 v[2:3], 11, v[2:3]
	v_lshl_add_u64 v[2:3], v[142:143], 0, v[2:3]
	global_load_dwordx4 v[22:25], v[2:3], off
	global_load_dwordx4 v[102:105], v[2:3], off offset:64
	s_add_i32 s21, s21, s61
	s_lshl_b32 s2, s21, 6
	s_and_b32 s33, s2, 0x1c0
	v_add_u32_e32 v1, s33, v115
	v_mad_u32_u24 v1, v1, s59, v117
	ds_read_b128 v[60:63], v1
	ds_read_b128 v[64:67], v1 offset:64
	v_add_u32_e32 v1, s33, v119
	v_mad_u32_u24 v1, v1, s59, v117
	s_sub_i32 s20, s21, s20
	s_add_i32 s21, s2, 64
	s_and_b32 s26, s21, 0x1c0
	s_add_i32 s21, s2, 0x80
	s_and_b32 s22, s21, 0x1c0
	s_addk_i32 s2, 0xc0
	s_and_b32 s2, s2, 0x1c0
	s_mul_i32 s20, s20, 31
	s_ashr_i32 s21, s20, 31
	s_lshl_b64 s[20:21], s[20:21], 2
	s_add_u32 s20, s36, s20
	s_addc_u32 s21, s23, s21
	v_readlane_b32 s0, v255, 10
	v_readlane_b32 s1, v255, 11
	s_waitcnt vmcnt(1) lgkmcnt(1)
	v_mfma_f32_16x16x32_bf16 v[60:63], v[60:63], v[22:25], 0
	s_waitcnt vmcnt(0) lgkmcnt(0)
	v_mfma_f32_16x16x32_bf16 v[84:87], v[64:67], v[102:105], v[60:63]
	s_nop 5
	ds_read_b128 v[60:63], v1
	ds_read_b128 v[64:67], v1 offset:64
	v_add_u32_e32 v1, s26, v115
	s_waitcnt lgkmcnt(1)
	v_mfma_f32_16x16x32_bf16 v[60:63], v[60:63], v[22:25], 0
	v_mad_u32_u24 v1, v1, s59, v117
	s_waitcnt lgkmcnt(0)
	v_mfma_f32_16x16x32_bf16 v[76:79], v[64:67], v[102:105], v[60:63]
	s_nop 4
	ds_read_b128 v[60:63], v1
	ds_read_b128 v[64:67], v1 offset:64
	v_add_u32_e32 v1, s26, v119
	v_mad_u32_u24 v1, v1, s59, v117
	s_waitcnt lgkmcnt(1)
	v_mfma_f32_16x16x32_bf16 v[60:63], v[60:63], v[22:25], 0
	s_waitcnt lgkmcnt(0)
	v_mfma_f32_16x16x32_bf16 v[80:83], v[64:67], v[102:105], v[60:63]
	s_nop 5
	ds_read_b128 v[60:63], v1
	ds_read_b128 v[64:67], v1 offset:64
	v_add_u32_e32 v1, s22, v115
	s_waitcnt lgkmcnt(1)
	v_mfma_f32_16x16x32_bf16 v[60:63], v[60:63], v[22:25], 0
	v_mad_u32_u24 v1, v1, s59, v117
	s_waitcnt lgkmcnt(0)
	v_mfma_f32_16x16x32_bf16 v[68:71], v[64:67], v[102:105], v[60:63]
	s_nop 4
	ds_read_b128 v[60:63], v1
	ds_read_b128 v[64:67], v1 offset:64
	v_add_u32_e32 v1, s22, v119
	v_mad_u32_u24 v1, v1, s59, v117
	s_waitcnt lgkmcnt(1)
	v_mfma_f32_16x16x32_bf16 v[60:63], v[60:63], v[22:25], 0
	s_waitcnt lgkmcnt(0)
	v_mfma_f32_16x16x32_bf16 v[72:75], v[64:67], v[102:105], v[60:63]
	s_nop 5
	ds_read_b128 v[60:63], v1
	ds_read_b128 v[64:67], v1 offset:64
	v_add_u32_e32 v1, s2, v115
	s_waitcnt lgkmcnt(1)
	v_mfma_f32_16x16x32_bf16 v[60:63], v[60:63], v[22:25], 0
	v_mad_u32_u24 v1, v1, s59, v117
	s_waitcnt lgkmcnt(0)
	v_mfma_f32_16x16x32_bf16 v[60:63], v[64:67], v[102:105], v[60:63]
	ds_read_b128 v[64:67], v1
	ds_read_b128 v[158:161], v1 offset:64
	v_add_u32_e32 v1, s2, v119
	v_mad_u32_u24 v1, v1, s59, v117
	s_waitcnt lgkmcnt(1)
	v_mfma_f32_16x16x32_bf16 v[64:67], v[64:67], v[22:25], 0
	s_or_b32 s2, s2, s60
	s_waitcnt lgkmcnt(0)
	v_mfma_f32_16x16x32_bf16 v[64:67], v[158:161], v[102:105], v[64:67]
	ds_read_b128 v[158:161], v1
	ds_read_b128 v[162:165], v1 offset:64
	global_load_dword v1, v99, s[20:21] offset:868
	global_load_dword v3, v98, s[20:21] offset:868
	global_load_dword v2, v96, s[20:21] offset:868
	s_waitcnt lgkmcnt(1)
	v_mfma_f32_16x16x32_bf16 v[22:25], v[158:161], v[22:25], 0
	s_waitcnt vmcnt(2)
	v_fmamk_f32 v1, v1, 0x3fb8aa3b, v84
	global_load_dword v84, v97, s[20:21] offset:868
	s_waitcnt lgkmcnt(0)
	v_mfma_f32_16x16x32_bf16 v[22:25], v[162:165], v[102:105], v[22:25]
	v_cndmask_b32_e64 v1, v220, v1, s[38:39]
	s_waitcnt vmcnt(0)
	v_fmamk_f32 v76, v84, 0x3fb8aa3b, v76
	global_load_dword v84, v93, s[20:21] offset:868
	v_fmamk_f32 v3, v3, 0x3fb8aa3b, v86
	v_cndmask_b32_e64 v59, v220, v3, s[42:43]
	global_load_dword v3, v94, s[20:21] offset:868
	v_cndmask_b32_e64 v76, v220, v76, s[46:47]
	s_waitcnt vmcnt(1)
	v_fmamk_f32 v77, v84, 0x3fb8aa3b, v77
	global_load_dword v84, v95, s[20:21] offset:868
	v_cndmask_b32_e64 v77, v220, v77, s[48:49]
	s_waitcnt vmcnt(0)
	v_fmamk_f32 v78, v84, 0x3fb8aa3b, v78
	v_cndmask_b32_e64 v84, v220, v78, s[50:51]
	global_load_dword v78, v92, s[20:21] offset:868
	v_fmac_f32_e32 v87, 0x3fb8aa3b, v3
	v_cndmask_b32_e64 v3, v220, v87, s[44:45]
	s_waitcnt vmcnt(0)
	v_fmac_f32_e32 v79, 0x3fb8aa3b, v78
	v_cndmask_b32_e64 v78, v220, v79, s[52:53]
	global_load_dword v79, v99, s[20:21] offset:992
	s_waitcnt vmcnt(0)
	v_fmamk_f32 v79, v79, 0x3fb8aa3b, v80
	global_load_dword v80, v96, s[20:21] offset:992
	v_cndmask_b32_e64 v79, v220, v79, s[38:39]
	s_waitcnt vmcnt(0)
	v_fmamk_f32 v80, v80, 0x3fb8aa3b, v81
	global_load_dword v81, v98, s[20:21] offset:992
	v_cndmask_b32_e64 v80, v220, v80, s[40:41]
	s_waitcnt vmcnt(0)
	v_fmamk_f32 v81, v81, 0x3fb8aa3b, v82
	v_cndmask_b32_e64 v82, v220, v81, s[42:43]
	global_load_dword v81, v94, s[20:21] offset:992
	s_waitcnt vmcnt(0)
	v_fmac_f32_e32 v83, 0x3fb8aa3b, v81
	v_cndmask_b32_e64 v81, v220, v83, s[44:45]
	global_load_dword v83, v97, s[20:21] offset:992
	s_waitcnt vmcnt(0)
	v_fmamk_f32 v68, v83, 0x3fb8aa3b, v68
	global_load_dword v83, v93, s[20:21] offset:992
	v_cndmask_b32_e64 v68, v220, v68, s[46:47]
	s_waitcnt vmcnt(0)
	v_fmamk_f32 v69, v83, 0x3fb8aa3b, v69
	global_load_dword v83, v95, s[20:21] offset:992
	v_cndmask_b32_e64 v69, v220, v69, s[48:49]
	s_waitcnt vmcnt(0)
	v_fmamk_f32 v70, v83, 0x3fb8aa3b, v70
	v_cndmask_b32_e64 v83, v220, v70, s[50:51]
	global_load_dword v70, v92, s[20:21] offset:992
	v_fmamk_f32 v2, v2, 0x3fb8aa3b, v85
	v_cndmask_b32_e64 v2, v220, v2, s[40:41]
	s_waitcnt vmcnt(0)
	v_fmac_f32_e32 v71, 0x3fb8aa3b, v70
	v_cndmask_b32_e64 v70, v220, v71, s[52:53]
	global_load_dword v71, v99, s[20:21] offset:1116
	v_max_f32_e32 v86, v83, v70
	v_max3_f32 v86, v68, v69, v86
	s_waitcnt vmcnt(0)
	v_fmamk_f32 v71, v71, 0x3fb8aa3b, v72
	global_load_dword v72, v96, s[20:21] offset:1116
	v_cndmask_b32_e64 v71, v220, v71, s[38:39]
	s_waitcnt vmcnt(0)
	v_fmamk_f32 v72, v72, 0x3fb8aa3b, v73
	global_load_dword v73, v98, s[20:21] offset:1116
	v_cndmask_b32_e64 v72, v220, v72, s[40:41]
	s_waitcnt vmcnt(0)
	v_fmamk_f32 v73, v73, 0x3fb8aa3b, v74
	v_cndmask_b32_e64 v74, v220, v73, s[42:43]
	global_load_dword v73, v94, s[20:21] offset:1116
	s_waitcnt vmcnt(0)
	v_fmac_f32_e32 v75, 0x3fb8aa3b, v73
	v_cndmask_b32_e64 v73, v220, v75, s[44:45]
	global_load_dword v75, v97, s[20:21] offset:1116
	s_waitcnt vmcnt(0)
	v_fmamk_f32 v60, v75, 0x3fb8aa3b, v60
	global_load_dword v75, v93, s[20:21] offset:1116
	v_cndmask_b32_e64 v60, v220, v60, s[46:47]
	s_waitcnt vmcnt(0)
	v_fmamk_f32 v61, v75, 0x3fb8aa3b, v61
	v_cndmask_b32_e64 v75, v220, v61, s[48:49]
	global_load_dword v61, v95, s[20:21] offset:1116
	s_waitcnt vmcnt(0)
	v_fmamk_f32 v61, v61, 0x3fb8aa3b, v62
	v_cndmask_b32_e64 v85, v220, v61, s[50:51]
	global_load_dword v61, v92, s[20:21] offset:1116
	s_waitcnt vmcnt(0)
	v_fmac_f32_e32 v63, 0x3fb8aa3b, v61
	global_load_dword v61, v99, s[20:21] offset:1240
	v_cndmask_b32_e64 v62, v220, v63, s[52:53]
	global_load_dword v63, v96, s[20:21] offset:1240
	s_waitcnt vmcnt(1)
	v_fmamk_f32 v61, v61, 0x3fb8aa3b, v64
	global_load_dword v64, v98, s[20:21] offset:1240
	v_cndmask_b32_e64 v61, v220, v61, s[38:39]
	s_waitcnt vmcnt(0)
	v_fmamk_f32 v64, v64, 0x3fb8aa3b, v66
	global_load_dword v66, v97, s[20:21] offset:1240
	v_cndmask_b32_e64 v64, v220, v64, s[42:43]
	s_waitcnt vmcnt(0)
	v_fmamk_f32 v22, v66, 0x3fb8aa3b, v22
	global_load_dword v66, v93, s[20:21] offset:1240
	v_fmamk_f32 v63, v63, 0x3fb8aa3b, v65
	global_load_dword v65, v94, s[20:21] offset:1240
	v_cndmask_b32_e64 v63, v220, v63, s[40:41]
	v_cndmask_b32_e64 v22, v220, v22, s[46:47]
	s_waitcnt vmcnt(1)
	v_fmamk_f32 v23, v66, 0x3fb8aa3b, v23
	global_load_dword v66, v95, s[20:21] offset:1240
	v_cndmask_b32_e64 v23, v220, v23, s[48:49]
	s_waitcnt vmcnt(0)
	v_fmamk_f32 v24, v66, 0x3fb8aa3b, v24
	global_load_dword v66, v92, s[20:21] offset:1240
	v_fmac_f32_e32 v67, 0x3fb8aa3b, v65
	v_cndmask_b32_e64 v65, v220, v67, s[44:45]
	v_max_f32_e32 v67, v84, v78
	v_max3_f32 v67, v76, v77, v67
	s_mov_b32 s20, 0xf149f2ca
	v_cndmask_b32_e64 v24, v220, v24, s[50:51]
	s_waitcnt vmcnt(0)
	v_fmac_f32_e32 v25, 0x3fb8aa3b, v66
	v_max_f32_e32 v66, v59, v3
	v_max3_f32 v66, v1, v2, v66
	v_max3_f32 v66, v66, s20, v67
	v_max_f32_e32 v67, v82, v81
	v_max3_f32 v67, v79, v80, v67
	v_max3_f32 v66, v66, v67, v86
	v_max_f32_e32 v67, v74, v73
	v_max_f32_e32 v86, v85, v62
	v_cndmask_b32_e64 v25, v220, v25, s[52:53]
	v_max3_f32 v67, v71, v72, v67
	v_max3_f32 v86, v60, v75, v86
	v_max3_f32 v66, v66, v67, v86
	v_max_f32_e32 v67, v64, v65
	v_max_f32_e32 v86, v24, v25
	v_max3_f32 v67, v61, v63, v67
	v_max3_f32 v86, v22, v23, v86
	v_max3_f32 v66, v66, v67, v86
	ds_bpermute_b32 v67, v145, v66
	s_waitcnt lgkmcnt(0)
	v_max_f32_e32 v67, v67, v67
	v_max_f32_e32 v66, v66, v67
	ds_bpermute_b32 v67, v149, v66
	s_waitcnt lgkmcnt(0)
	v_max3_f32 v159, v66, v67, s20
	v_sub_f32_e32 v1, v1, v159
	v_exp_f32_e32 v67, v1
	v_sub_f32_e32 v2, v2, v159
	v_exp_f32_e32 v2, v2
	v_sub_f32_e32 v59, v59, v159
	v_exp_f32_e32 v59, v59
	v_sub_f32_e32 v3, v3, v159
	v_exp_f32_e32 v3, v3
	v_sub_f32_e32 v76, v76, v159
	v_add_f32_e32 v1, 0, v67
	v_exp_f32_e32 v76, v76
	v_sub_f32_e32 v77, v77, v159
	v_add_f32_e32 v1, v2, v1
	v_exp_f32_e32 v77, v77
	v_sub_f32_e32 v84, v84, v159
	v_add_f32_e32 v1, v59, v1
	v_exp_f32_e32 v84, v84
	v_sub_f32_e32 v78, v78, v159
	v_add_f32_e32 v1, v3, v1
	v_exp_f32_e32 v78, v78
	v_sub_f32_e32 v79, v79, v159
	v_add_f32_e32 v1, v76, v1
	v_exp_f32_e32 v86, v79
	v_sub_f32_e32 v79, v80, v159
	v_add_f32_e32 v1, v77, v1
	v_exp_f32_e32 v80, v79
	v_sub_f32_e32 v79, v82, v159
	v_add_f32_e32 v1, v84, v1
	v_exp_f32_e32 v82, v79
	v_sub_f32_e32 v79, v81, v159
	v_add_f32_e32 v1, v78, v1
	v_exp_f32_e32 v81, v79
	v_sub_f32_e32 v68, v68, v159
	v_add_f32_e32 v1, v86, v1
	v_exp_f32_e32 v87, v68
	v_sub_f32_e32 v68, v69, v159
	v_add_f32_e32 v1, v80, v1
	v_exp_f32_e32 v92, v68
	v_sub_f32_e32 v68, v83, v159
	v_add_f32_e32 v1, v82, v1
	v_exp_f32_e32 v83, v68
	v_sub_f32_e32 v68, v70, v159
	v_add_f32_e32 v1, v81, v1
	v_exp_f32_e32 v93, v68
	v_sub_f32_e32 v68, v71, v159
	v_add_f32_e32 v1, v87, v1
	v_exp_f32_e32 v94, v68
	v_sub_f32_e32 v68, v72, v159
	v_add_f32_e32 v1, v92, v1
	v_exp_f32_e32 v95, v68
	v_sub_f32_e32 v68, v74, v159
	v_add_f32_e32 v1, v83, v1
	v_exp_f32_e32 v96, v68
	v_sub_f32_e32 v68, v73, v159
	v_add_f32_e32 v1, v93, v1
	v_exp_f32_e32 v97, v68
	v_sub_f32_e32 v60, v60, v159
	v_add_f32_e32 v1, v94, v1
	v_exp_f32_e32 v98, v60
	v_sub_f32_e32 v60, v75, v159
	v_add_f32_e32 v1, v95, v1
	v_exp_f32_e32 v99, v60
	v_sub_f32_e32 v60, v85, v159
	v_add_f32_e32 v1, v96, v1
	v_exp_f32_e32 v85, v60
	v_sub_f32_e32 v60, v62, v159
	v_add_f32_e32 v1, v97, v1
	v_exp_f32_e32 v101, v60
	v_sub_f32_e32 v60, v61, v159
	v_add_f32_e32 v1, v98, v1
	v_exp_f32_e32 v102, v60
	v_sub_f32_e32 v60, v63, v159
	v_add_f32_e32 v1, v99, v1
	v_exp_f32_e32 v103, v60
	v_sub_f32_e32 v60, v64, v159
	v_add_f32_e32 v1, v85, v1
	v_exp_f32_e32 v104, v60
	v_sub_f32_e32 v60, v65, v159
	v_add_f32_e32 v1, v101, v1
	v_exp_f32_e32 v105, v60
	v_sub_f32_e32 v22, v22, v159
	v_add_f32_e32 v1, v102, v1
	v_exp_f32_e32 v106, v22
	v_sub_f32_e32 v22, v23, v159
	v_add_f32_e32 v1, v103, v1
	v_exp_f32_e32 v107, v22
	v_sub_f32_e32 v22, v24, v159
	s_or_b32 s20, s33, s60
	v_add_f32_e32 v1, v104, v1
	v_exp_f32_e32 v147, v22
	v_sub_f32_e32 v22, v25, v159
	v_cvt_pk_bf16_f32 v60, v67, v2
	v_lshl_add_u32 v2, s20, 1, v121
	v_sub_f32_e32 v66, 0xf149f2ca, v159
	v_add_f32_e32 v1, v105, v1
	v_exp_f32_e32 v148, v22
	v_cvt_pk_bf16_f32 v61, v59, v3
	v_add_u32_e32 v3, v2, v123
	v_add_f32_e32 v1, v106, v1
	v_exp_f32_e32 v22, v66
	v_cvt_pk_bf16_f32 v62, v76, v77
	v_cvt_pk_bf16_f32 v63, v84, v78
	ds_read2_b64 v[64:67], v3 offset1:4
	v_add_u32_e32 v59, 0x4000, v3
	v_add_u32_e32 v3, 0x8000, v3
	v_add_u32_e32 v2, v2, v125
	v_add_f32_e32 v1, v107, v1
	ds_read2_b64 v[68:71], v59 offset0:32 offset1:36
	ds_read2_b64 v[72:75], v3 offset0:64 offset1:68
	ds_read2_b64 v[76:79], v2 offset1:4
	v_add_f32_e32 v1, v147, v1
	v_add_f32_e32 v1, v148, v1
	ds_bpermute_b32 v23, v145, v1
	s_or_b32 s20, s26, s60
	v_mul_f32_e32 v22, 0, v22
	v_lshl_add_u32 v2, s20, 1, v121
	v_mov_b32_e32 v24, v22
	s_waitcnt lgkmcnt(0)
	v_add_f32_e32 v1, v1, v23
	v_mov_b32_e32 v23, v22
	v_mov_b32_e32 v25, v22
	v_add_u32_e32 v3, v2, v123
	v_add_u32_e32 v2, v2, v125
	v_mfma_f32_16x16x32_bf16 v[64:67], v[64:67], v[60:63], v[22:25]
	s_or_b32 s20, s22, s60
	ds_bpermute_b32 v158, v149, v1
	v_mfma_f32_16x16x32_bf16 v[68:71], v[68:71], v[60:63], v[22:25]
	v_mfma_f32_16x16x32_bf16 v[72:75], v[72:75], v[60:63], v[22:25]
	v_mfma_f32_16x16x32_bf16 v[60:63], v[76:79], v[60:63], v[22:25]
	v_cvt_pk_bf16_f32 v76, v86, v80
	v_cvt_pk_bf16_f32 v77, v82, v81
	v_cvt_pk_bf16_f32 v78, v87, v92
	v_cvt_pk_bf16_f32 v79, v83, v93
	ds_read2_b64 v[80:83], v3 offset1:4
	s_nop 1
	v_add_u32_e32 v23, 0x4000, v3
	s_waitcnt lgkmcnt(0)
	v_mfma_f32_16x16x32_bf16 v[64:67], v[80:83], v[76:79], v[64:67]
	ds_read2_b64 v[80:83], v23 offset0:32 offset1:36
	v_add_u32_e32 v3, 0x8000, v3
	s_waitcnt lgkmcnt(0)
	v_mfma_f32_16x16x32_bf16 v[68:71], v[80:83], v[76:79], v[68:71]
	ds_read2_b64 v[80:83], v3 offset0:64 offset1:68
	s_waitcnt lgkmcnt(0)
	v_mfma_f32_16x16x32_bf16 v[72:75], v[80:83], v[76:79], v[72:75]
	ds_read2_b64 v[80:83], v2 offset1:4
	v_lshl_add_u32 v2, s20, 1, v121
	v_add_u32_e32 v3, v2, v123
	s_waitcnt lgkmcnt(0)
	v_mfma_f32_16x16x32_bf16 v[60:63], v[80:83], v[76:79], v[60:63]
	v_cvt_pk_bf16_f32 v76, v94, v95
	v_cvt_pk_bf16_f32 v77, v96, v97
	v_cvt_pk_bf16_f32 v78, v98, v99
	v_cvt_pk_bf16_f32 v79, v85, v101
	ds_read2_b64 v[80:83], v3 offset1:4
	v_add_u32_e32 v23, 0x4000, v3
	s_waitcnt lgkmcnt(0)
	v_mfma_f32_16x16x32_bf16 v[64:67], v[80:83], v[76:79], v[64:67]
	ds_read2_b64 v[80:83], v23 offset0:32 offset1:36
	v_add_u32_e32 v3, 0x8000, v3
	v_add_u32_e32 v2, v2, v125
	s_waitcnt lgkmcnt(0)
	v_mfma_f32_16x16x32_bf16 v[68:71], v[80:83], v[76:79], v[68:71]
	ds_read2_b64 v[80:83], v3 offset0:64 offset1:68
	s_waitcnt lgkmcnt(0)
	v_mfma_f32_16x16x32_bf16 v[72:75], v[80:83], v[76:79], v[72:75]
	ds_read2_b64 v[80:83], v2 offset1:4
	v_lshl_add_u32 v2, s2, 1, v121
	v_add_u32_e32 v3, v2, v123
	s_waitcnt lgkmcnt(0)
	v_mfma_f32_16x16x32_bf16 v[76:79], v[80:83], v[76:79], v[60:63]
	v_cvt_pk_bf16_f32 v80, v102, v103
	v_cvt_pk_bf16_f32 v81, v104, v105
	v_cvt_pk_bf16_f32 v82, v106, v107
	v_cvt_pk_bf16_f32 v83, v147, v148
	s_nop 2
	ds_read2_b64 v[60:63], v3 offset1:4
	v_add_u32_e32 v23, 0x4000, v3
	s_waitcnt lgkmcnt(0)
	v_mfma_f32_16x16x32_bf16 v[60:63], v[60:63], v[80:83], v[64:67]
	s_nop 2
	ds_read2_b64 v[64:67], v23 offset0:32 offset1:36
	v_add_u32_e32 v3, 0x8000, v3
	v_add_u32_e32 v2, v2, v125
	s_waitcnt lgkmcnt(0)
	v_mfma_f32_16x16x32_bf16 v[64:67], v[64:67], v[80:83], v[68:71]
	s_nop 2
	ds_read2_b64 v[68:71], v3 offset0:64 offset1:68
	s_waitcnt lgkmcnt(0)
	v_mfma_f32_16x16x32_bf16 v[68:71], v[68:71], v[80:83], v[72:75]
	s_nop 2
	ds_read2_b64 v[72:75], v2 offset1:4
	s_waitcnt lgkmcnt(0)
	v_mfma_f32_16x16x32_bf16 v[72:75], v[72:75], v[80:83], v[76:79]
	s_barrier
	s_and_saveexec_b64 s[20:21], s[0:1]
	s_xor_b64 s[20:21], exec, s[20:21]
	s_cbranch_execz .LBB0_130
	s_lshl_b64 s[22:23], s[56:57], 15
	v_lshl_add_u64 v[2:3], v[130:131], 0, s[22:23]
	s_movk_i32 s2, 0x90
	s_movk_i32 s26, 0x5ff
	v_mov_b32_e32 v23, v192
	v_ashrrev_i32_e32 v24, 3, v23
	v_ashrrev_i32_e32 v25, 31, v24
	v_lshlrev_b64 v[176:177], 7, v[24:25]
	v_lshl_add_u64 v[176:177], v[2:3], 0, v[176:177]
	global_load_dwordx4 v[76:79], v[176:177], off
	v_mad_u32_u24 v168, v24, s2, v110
	v_add_u32_e32 v23, 0x200, v192
	v_ashrrev_i32_e32 v24, 3, v23
	v_ashrrev_i32_e32 v25, 31, v24
	v_lshlrev_b64 v[176:177], 7, v[24:25]
	v_lshl_add_u64 v[176:177], v[2:3], 0, v[176:177]
	global_load_dwordx4 v[80:83], v[176:177], off
	v_mad_u32_u24 v169, v24, s2, v110
	v_add_u32_e32 v23, 0x400, v192
	v_ashrrev_i32_e32 v24, 3, v23
	v_ashrrev_i32_e32 v25, 31, v24
	v_lshlrev_b64 v[176:177], 7, v[24:25]
	v_lshl_add_u64 v[176:177], v[2:3], 0, v[176:177]
	global_load_dwordx4 v[84:87], v[176:177], off
	v_mad_u32_u24 v170, v24, s2, v110
	v_add_u32_e32 v23, 0x600, v192
	v_ashrrev_i32_e32 v24, 3, v23
	v_ashrrev_i32_e32 v25, 31, v24
	v_lshlrev_b64 v[176:177], 7, v[24:25]
	v_lshl_add_u64 v[176:177], v[2:3], 0, v[176:177]
	global_load_dwordx4 v[92:95], v[176:177], off
	v_mad_u32_u24 v171, v24, s2, v110
	v_lshl_add_u64 v[2:3], v[132:133], 0, s[22:23]
	s_movk_i32 s2, 0x210
	v_mov_b32_e32 v23, v192
	v_ashrrev_i32_e32 v24, 5, v23
	v_ashrrev_i32_e32 v25, 31, v24
	v_lshlrev_b64 v[176:177], 9, v[24:25]
	v_lshl_add_u64 v[176:177], v[2:3], 0, v[176:177]
	global_load_dwordx4 v[96:99], v[176:177], off
	v_mad_u32_u24 v172, v24, s2, v134
	v_add_u32_e32 v23, 0x200, v192
	v_ashrrev_i32_e32 v24, 5, v23
	v_ashrrev_i32_e32 v25, 31, v24
	v_lshlrev_b64 v[176:177], 9, v[24:25]
	v_lshl_add_u64 v[176:177], v[2:3], 0, v[176:177]
	global_load_dwordx4 v[104:107], v[176:177], off
	v_mad_u32_u24 v173, v24, s2, v134
	v_add_u32_e32 v23, 0x400, v192
	v_ashrrev_i32_e32 v24, 5, v23
	v_ashrrev_i32_e32 v25, 31, v24
	v_lshlrev_b64 v[176:177], 9, v[24:25]
	v_lshl_add_u64 v[176:177], v[2:3], 0, v[176:177]
	global_load_dwordx4 v[160:163], v[176:177], off
	v_mad_u32_u24 v174, v24, s2, v134
	v_add_u32_e32 v23, 0x600, v192
	v_ashrrev_i32_e32 v24, 5, v23
	v_ashrrev_i32_e32 v25, 31, v24
	v_lshlrev_b64 v[176:177], 9, v[24:25]
	v_lshl_add_u64 v[176:177], v[2:3], 0, v[176:177]
	global_load_dwordx4 v[164:167], v[176:177], off
	v_mad_u32_u24 v175, v24, s2, v134
	s_waitcnt vmcnt(7)
	ds_write_b128 v168, v[76:79]
	s_waitcnt vmcnt(6)
	ds_write_b128 v169, v[80:83]
	s_waitcnt vmcnt(5)
	ds_write_b128 v170, v[84:87]
	s_waitcnt vmcnt(4)
	ds_write_b128 v171, v[92:95]
	s_waitcnt vmcnt(3)
	ds_write_b128 v172, v[96:99]
	s_waitcnt vmcnt(2)
	ds_write_b128 v173, v[104:107]
	s_waitcnt vmcnt(1)
	ds_write_b128 v174, v[160:163]
	s_waitcnt vmcnt(0)
	ds_write_b128 v175, v[164:167]
